# v31 + residual-GEMM epilogue: all 8 old-XG loads of the second row half issued before one wait (was: 1 load, full drain, then 7)
# speedup vs baseline: 1.0038x; 1.0038x over previous
; __host__ __device__ __forceinline__ unsigned img_off(unsigned row, unsigned col, unsigned KT) { return (((row >> 8) * KT + (col >> 6)) << 14) + (((row >> 7) & 1u) << 13) + hl_off(row & 127u, col & 63u); }
;     __device__ __forceinline__ void operator()(const f32x4 (&acc)[2][2][4][2], const Unit& u, int wr, int wc, int fr, int fq) const {
;     ...
;         bf16_t* gpb = XG + img_off((unsigned)(u.pm * BM + wr * 64 + fr), (unsigned)col0, 16u);
; #pragma unroll
;         for (int ai = 0; ai < 2; ++ai) {
;         u32x4 xin[2][4][2];
; #pragma unroll
;             for (int m = 0; m < 4; ++m)
; #pragma unroll
;                 for (int bj = 0; bj < 2; ++bj) xin[ai][m][bj] = *(const u32x4*)(gpb + ai * 8192 + m * 1024 + bj * 2 * 16384);
; #pragma unroll
;             for (int m = 0; m < 4; ++m) {
;                 const int row = u.pm * BM + ai * HALF + wr * 64 + m * 16 + fr;
;                 bf16_t* gp = gpb + ai * 8192 + m * 1024;
;                 float q = 0.f;
; #pragma unroll
;                 for (int bj = 0; bj < 2; ++bj) {
;                     const u32x4 xr = xin[ai][m][bj];
;                     f32x4 x0, x1;
;                     x0[0] = __builtin_bit_cast(float, xr.x << 16); x0[1] = __builtin_bit_cast(float, xr.x & 0xffff0000u); x0[2] = __builtin_bit_cast(float, xr.y << 16); x0[3] = __builtin_bit_cast(float, xr.y & 0xffff0000u);
;                     x1[0] = __builtin_bit_cast(float, xr.z << 16); x1[1] = __builtin_bit_cast(float, xr.z & 0xffff0000u); x1[2] = __builtin_bit_cast(float, xr.w << 16); x1[3] = __builtin_bit_cast(float, xr.w & 0xffff0000u);
.LBB0_257:
	s_or_b64 exec, exec, s[56:57]
	v_add_co_u32_e32 v148, vcc, 0x4000, v218
	s_nop 1
	v_addc_co_u32_e32 v149, vcc, 0, v219, vcc
	global_load_dwordx4 v[140:143], v[148:149], off
	v_add_co_u32_e32 v138, vcc, 0x14000, v218
	s_nop 1
	v_addc_co_u32_e32 v139, vcc, 0, v219, vcc
	global_load_dwordx4 v[144:147], v[138:139], off
	global_load_dwordx4 v[134:137], v[148:149], off offset:2048
	global_load_dwordx4 v[130:133], v[138:139], off offset:2048
	v_add_co_u32_e32 v114, vcc, 0x5000, v218
	s_waitcnt lgkmcnt(0)
	s_nop 0
	v_addc_co_u32_e32 v115, vcc, 0, v219, vcc
	v_add_co_u32_e32 v116, vcc, 0x15000, v218
	global_load_dwordx4 v[126:129], v[114:115], off
	s_nop 0
	v_addc_co_u32_e32 v117, vcc, 0, v219, vcc
	global_load_dwordx4 v[122:125], v[116:117], off
	global_load_dwordx4 v[118:121], v[114:115], off offset:2048
	s_nop 0
	global_load_dwordx4 v[114:117], v[116:117], off offset:2048
	s_waitcnt vmcnt(0)
	v_lshlrev_b32_e32 v150, 16, v140
	v_and_b32_e32 v151, 0xffff0000, v140


; __device__ __forceinline__ unsigned cvt_pk_bf16(float lo, float hi) { unsigned r; asm volatile("v_cvt_pk_bf16_f32 %0, %1, %2" : "=v"(r) : "v"(lo), "v"(hi)); return r; }
;     __device__ __forceinline__ void operator()(const f32x4 (&acc)[2][2][4][2], const Unit& u, int wr, int wc, int fr, int fq) const {
;     ...
;             for (int m = 0; m < 4; ++m) {
;                 const int row = u.pm * BM + ai * HALF + wr * 64 + m * 16 + fr;
;                 bf16_t* gp = gpb + ai * 8192 + m * 1024;
;                 float q = 0.f;
; #pragma unroll
;                 for (int bj = 0; bj < 2; ++bj) {
;                     const u32x4 xr = xin[ai][m][bj];
;                     f32x4 x0, x1;
;                     x0[0] = __builtin_bit_cast(float, xr.x << 16); x0[1] = __builtin_bit_cast(float, xr.x & 0xffff0000u); x0[2] = __builtin_bit_cast(float, xr.y << 16); x0[3] = __builtin_bit_cast(float, xr.y & 0xffff0000u);
;                     x1[0] = __builtin_bit_cast(float, xr.z << 16); x1[1] = __builtin_bit_cast(float, xr.z & 0xffff0000u); x1[2] = __builtin_bit_cast(float, xr.w << 16); x1[3] = __builtin_bit_cast(float, xr.w & 0xffff0000u);
;                     const f32x4 y0 = x0 * vr[bj][0] + vt[bj][0] * acc[ai][bj][m][0], y1 = x1 * vr[bj][1] + vt[bj][1] * acc[ai][bj][m][1];
;                     u32x4 w; w.x = cvt_pk_bf16(y0[0], y0[1]); w.y = cvt_pk_bf16(y0[2], y0[3]); w.z = cvt_pk_bf16(y1[0], y1[1]); w.w = cvt_pk_bf16(y1[2], y1[3]);
;                     *(u32x4*)(gp + bj * 2 * 16384) = w;
;                     const f32x4 z0 = y0 * vi[bj][0], z1 = y1 * vi[bj][1];
;                     q += (z0[0] * z0[0] + z0[1] * z0[1]) + (z0[2] * z0[2] + z0[3] * z0[3]) + (z1[0] * z1[0] + z1[1] * z1[1]) + (z1[2] * z1[2] + z1[3] * z1[3]);
;                 }
;                 q += __shfl_xor(q, 16); q += __shfl_xor(q, 32);
;                 if (fq == 0) ss[(size_t)row * 16 + u.pn * 4 + wc] = q;
	v_lshlrev_b32_e32 v140, 16, v141
	v_and_b32_e32 v141, 0xffff0000, v141
	v_lshlrev_b32_e32 v152, 16, v142
	v_and_b32_e32 v153, 0xffff0000, v142
	v_lshlrev_b32_e32 v142, 16, v143
	v_and_b32_e32 v143, 0xffff0000, v143
	v_pk_mul_f32 v[140:141], v[108:109], v[140:141]
	v_pk_mul_f32 v[150:151], v[106:107], v[150:151]
	v_pk_fma_f32 v[72:73], v[72:73], v[112:113], v[140:141]
	v_pk_mul_f32 v[140:141], v[98:99], v[152:153]
	v_pk_mul_f32 v[142:143], v[100:101], v[142:143]
	v_pk_fma_f32 v[70:71], v[70:71], v[110:111], v[150:151]
	v_pk_fma_f32 v[142:143], v[60:61], v[104:105], v[142:143]
	v_pk_fma_f32 v[140:141], v[58:59], v[102:103], v[140:141]
	v_cvt_pk_bf16_f32 v58, v70, v71
	v_cvt_pk_bf16_f32 v59, v72, v73
	s_nop 0
	v_cvt_pk_bf16_f32 v60, v140, v141
	v_cvt_pk_bf16_f32 v61, v142, v143
	global_store_dwordx4 v[148:149], v[58:61], off
	s_nop 1
	v_pk_mul_f32 v[58:59], v[96:97], v[72:73]
	v_pk_mul_f32 v[60:61], v[94:95], v[70:71]
	v_mul_f32_e32 v59, v59, v59
	v_mul_f32_e32 v61, v61, v61
	v_pk_mul_f32 v[72:73], v[90:91], v[140:141]
	v_fmac_f32_e32 v61, v60, v60
	v_fmac_f32_e32 v59, v58, v58
	v_add_f32_e32 v58, v61, v59
	v_mul_f32_e32 v59, v73, v73
	v_pk_mul_f32 v[70:71], v[92:93], v[142:143]
	v_fmac_f32_e32 v59, v72, v72
	v_add_f32_e32 v58, v59, v58
	v_mul_f32_e32 v59, v71, v71
	v_fmac_f32_e32 v59, v70, v70
	v_add_f32_e32 v140, v59, v58
	s_waitcnt vmcnt(7)
	v_lshlrev_b32_e32 v58, 16, v144
	v_and_b32_e32 v59, 0xffff0000, v144
	v_lshlrev_b32_e32 v60, 16, v145
	v_and_b32_e32 v61, 0xffff0000, v145
	v_lshlrev_b32_e32 v70, 16, v146
	v_and_b32_e32 v71, 0xffff0000, v146
	v_lshlrev_b32_e32 v72, 16, v147
	v_and_b32_e32 v73, 0xffff0000, v147
	v_pk_mul_f32 v[58:59], v[86:87], v[58:59]
	v_pk_mul_f32 v[60:61], v[88:89], v[60:61]
	v_pk_fma_f32 v[54:55], v[54:55], v[82:83], v[58:59]
	v_pk_fma_f32 v[56:57], v[56:57], v[84:85], v[60:61]
	v_pk_mul_f32 v[58:59], v[74:75], v[70:71]
	v_pk_mul_f32 v[60:61], v[76:77], v[72:73]
	v_pk_fma_f32 v[58:59], v[50:51], v[78:79], v[58:59]
	v_pk_fma_f32 v[60:61], v[52:53], v[80:81], v[60:61]
	v_cvt_pk_bf16_f32 v50, v54, v55
	v_cvt_pk_bf16_f32 v51, v56, v57
	v_cvt_pk_bf16_f32 v52, v58, v59
	s_nop 0
	v_cvt_pk_bf16_f32 v53, v60, v61
	global_store_dwordx4 v[138:139], v[50:53], off
	s_nop 1
	v_pk_mul_f32 v[50:51], v[68:69], v[56:57]
	v_pk_mul_f32 v[52:53], v[66:67], v[54:55]
	v_mul_f32_e32 v51, v51, v51
	v_mul_f32_e32 v53, v53, v53
	v_pk_mul_f32 v[56:57], v[62:63], v[58:59]
	v_fmac_f32_e32 v53, v52, v52
	v_fmac_f32_e32 v51, v50, v50
	v_add_f32_e32 v50, v53, v51
	v_mul_f32_e32 v51, v57, v57
	v_pk_mul_f32 v[54:55], v[64:65], v[60:61]
	v_fmac_f32_e32 v51, v56, v56
	v_add_f32_e32 v50, v51, v50
	v_mul_f32_e32 v51, v55, v55
	v_fmac_f32_e32 v51, v54, v54
	v_add_f32_e32 v50, v51, v50
	v_add_f32_e32 v50, v140, v50
	ds_bpermute_b32 v51, v162, v50
	s_waitcnt lgkmcnt(0)
	v_add_f32_e32 v50, v50, v51
	ds_bpermute_b32 v51, v163, v50
	s_and_saveexec_b64 s[56:57], s[38:39]
	s_cbranch_execz .LBB0_259
	v_add_u32_e32 v52, 0x80, v216
	v_ashrrev_i32_e32 v53, 31, v52
	v_readlane_b32 s28, v252, 39
	s_waitcnt lgkmcnt(0)
	v_add_f32_e32 v54, v50, v51
	v_lshlrev_b64 v[50:51], 6, v[52:53]
	v_readlane_b32 s29, v252, 40
	s_lshl_b32 s64, s76, 2
	s_nop 0
	v_lshl_add_u64 v[50:51], s[28:29], 0, v[50:51]
	v_lshl_add_u64 v[50:51], s[54:55], 2, v[50:51]
	v_lshl_add_u64 v[50:51], v[50:51], 0, s[64:65]
	global_store_dword v[50:51], v54, off

; __host__ __device__ __forceinline__ unsigned img_off(unsigned row, unsigned col, unsigned KT) { return (((row >> 8) * KT + (col >> 6)) << 14) + (((row >> 7) & 1u) << 13) + hl_off(row & 127u, col & 63u); }
;     __device__ __forceinline__ void operator()(const f32x4 (&acc)[2][2][4][2], const Unit& u, int wr, int wc, int fr, int fq) const {
;     ...
;         bf16_t* gpb = XG + img_off((unsigned)(u.pm * BM + wr * 64 + fr), (unsigned)col0, 16u);
; #pragma unroll
;         for (int ai = 0; ai < 2; ++ai) {
;         u32x4 xin[2][4][2];
; #pragma unroll
;             for (int m = 0; m < 4; ++m)
; #pragma unroll
;                 for (int bj = 0; bj < 2; ++bj) xin[ai][m][bj] = *(const u32x4*)(gpb + ai * 8192 + m * 1024 + bj * 2 * 16384);
; #pragma unroll
;             for (int m = 0; m < 4; ++m) {
;                 const int row = u.pm * BM + ai * HALF + wr * 64 + m * 16 + fr;
;                 bf16_t* gp = gpb + ai * 8192 + m * 1024;
;                 float q = 0.f;
; #pragma unroll
;                 for (int bj = 0; bj < 2; ++bj) {
;                     const u32x4 xr = xin[ai][m][bj];
;                     f32x4 x0, x1;
;                     x0[0] = __builtin_bit_cast(float, xr.x << 16); x0[1] = __builtin_bit_cast(float, xr.x & 0xffff0000u); x0[2] = __builtin_bit_cast(float, xr.y << 16); x0[3] = __builtin_bit_cast(float, xr.y & 0xffff0000u);
;                     x1[0] = __builtin_bit_cast(float, xr.z << 16); x1[1] = __builtin_bit_cast(float, xr.z & 0xffff0000u); x1[2] = __builtin_bit_cast(float, xr.w << 16); x1[3] = __builtin_bit_cast(float, xr.w & 0xffff0000u);
.LBB0_387:
	s_or_b64 exec, exec, s[54:55]
	v_add_co_u32_e32 v148, vcc, 0x4000, v218
	s_nop 1
	v_addc_co_u32_e32 v149, vcc, 0, v219, vcc
	global_load_dwordx4 v[140:143], v[148:149], off
	v_add_co_u32_e32 v138, vcc, 0x14000, v218
	s_nop 1
	v_addc_co_u32_e32 v139, vcc, 0, v219, vcc
	global_load_dwordx4 v[144:147], v[138:139], off
	global_load_dwordx4 v[134:137], v[148:149], off offset:2048
	global_load_dwordx4 v[130:133], v[138:139], off offset:2048
	v_add_co_u32_e32 v114, vcc, 0x5000, v218
	s_waitcnt lgkmcnt(0)
	s_nop 0
	v_addc_co_u32_e32 v115, vcc, 0, v219, vcc
	v_add_co_u32_e32 v116, vcc, 0x15000, v218
	global_load_dwordx4 v[126:129], v[114:115], off
	s_nop 0
	v_addc_co_u32_e32 v117, vcc, 0, v219, vcc
	global_load_dwordx4 v[122:125], v[116:117], off
	global_load_dwordx4 v[118:121], v[114:115], off offset:2048
	s_nop 0
	global_load_dwordx4 v[114:117], v[116:117], off offset:2048
	s_waitcnt vmcnt(0)
	v_lshlrev_b32_e32 v150, 16, v140
	v_and_b32_e32 v151, 0xffff0000, v140


; __device__ __forceinline__ unsigned cvt_pk_bf16(float lo, float hi) { unsigned r; asm volatile("v_cvt_pk_bf16_f32 %0, %1, %2" : "=v"(r) : "v"(lo), "v"(hi)); return r; }
;     __device__ __forceinline__ void operator()(const f32x4 (&acc)[2][2][4][2], const Unit& u, int wr, int wc, int fr, int fq) const {
;     ...
;             for (int m = 0; m < 4; ++m) {
;                 const int row = u.pm * BM + ai * HALF + wr * 64 + m * 16 + fr;
;                 bf16_t* gp = gpb + ai * 8192 + m * 1024;
;                 float q = 0.f;
; #pragma unroll
;                 for (int bj = 0; bj < 2; ++bj) {
;                     const u32x4 xr = xin[ai][m][bj];
;                     f32x4 x0, x1;
;                     x0[0] = __builtin_bit_cast(float, xr.x << 16); x0[1] = __builtin_bit_cast(float, xr.x & 0xffff0000u); x0[2] = __builtin_bit_cast(float, xr.y << 16); x0[3] = __builtin_bit_cast(float, xr.y & 0xffff0000u);
;                     x1[0] = __builtin_bit_cast(float, xr.z << 16); x1[1] = __builtin_bit_cast(float, xr.z & 0xffff0000u); x1[2] = __builtin_bit_cast(float, xr.w << 16); x1[3] = __builtin_bit_cast(float, xr.w & 0xffff0000u);
;                     const f32x4 y0 = x0 * vr[bj][0] + vt[bj][0] * acc[ai][bj][m][0], y1 = x1 * vr[bj][1] + vt[bj][1] * acc[ai][bj][m][1];
;                     u32x4 w; w.x = cvt_pk_bf16(y0[0], y0[1]); w.y = cvt_pk_bf16(y0[2], y0[3]); w.z = cvt_pk_bf16(y1[0], y1[1]); w.w = cvt_pk_bf16(y1[2], y1[3]);
;                     *(u32x4*)(gp + bj * 2 * 16384) = w;
;                     const f32x4 z0 = y0 * vi[bj][0], z1 = y1 * vi[bj][1];
;                     q += (z0[0] * z0[0] + z0[1] * z0[1]) + (z0[2] * z0[2] + z0[3] * z0[3]) + (z1[0] * z1[0] + z1[1] * z1[1]) + (z1[2] * z1[2] + z1[3] * z1[3]);
;                 }
;                 q += __shfl_xor(q, 16); q += __shfl_xor(q, 32);
;                 if (fq == 0) ss[(size_t)row * 16 + u.pn * 4 + wc] = q;
	v_lshlrev_b32_e32 v140, 16, v141
	v_and_b32_e32 v141, 0xffff0000, v141
	v_lshlrev_b32_e32 v152, 16, v142
	v_and_b32_e32 v153, 0xffff0000, v142
	v_lshlrev_b32_e32 v142, 16, v143
	v_and_b32_e32 v143, 0xffff0000, v143
	v_pk_mul_f32 v[140:141], v[108:109], v[140:141]
	v_pk_mul_f32 v[150:151], v[106:107], v[150:151]
	v_pk_fma_f32 v[72:73], v[72:73], v[112:113], v[140:141]
	v_pk_mul_f32 v[140:141], v[98:99], v[152:153]
	v_pk_mul_f32 v[142:143], v[100:101], v[142:143]
	v_pk_fma_f32 v[70:71], v[70:71], v[110:111], v[150:151]
	v_pk_fma_f32 v[142:143], v[60:61], v[104:105], v[142:143]
	v_pk_fma_f32 v[140:141], v[58:59], v[102:103], v[140:141]
	v_cvt_pk_bf16_f32 v58, v70, v71
	v_cvt_pk_bf16_f32 v59, v72, v73
	s_nop 0
	v_cvt_pk_bf16_f32 v60, v140, v141
	v_cvt_pk_bf16_f32 v61, v142, v143
	global_store_dwordx4 v[148:149], v[58:61], off
	s_nop 1
	v_pk_mul_f32 v[58:59], v[96:97], v[72:73]
	v_pk_mul_f32 v[60:61], v[94:95], v[70:71]
	v_mul_f32_e32 v59, v59, v59
	v_mul_f32_e32 v61, v61, v61
	v_pk_mul_f32 v[72:73], v[90:91], v[140:141]
	v_fmac_f32_e32 v61, v60, v60
	v_fmac_f32_e32 v59, v58, v58
	v_add_f32_e32 v58, v61, v59
	v_mul_f32_e32 v59, v73, v73
	v_pk_mul_f32 v[70:71], v[92:93], v[142:143]
	v_fmac_f32_e32 v59, v72, v72
	v_add_f32_e32 v58, v59, v58
	v_mul_f32_e32 v59, v71, v71
	v_fmac_f32_e32 v59, v70, v70
	v_add_f32_e32 v140, v59, v58
	s_waitcnt vmcnt(7)
	v_lshlrev_b32_e32 v58, 16, v144
	v_and_b32_e32 v59, 0xffff0000, v144
	v_lshlrev_b32_e32 v60, 16, v145
	v_and_b32_e32 v61, 0xffff0000, v145
	v_lshlrev_b32_e32 v70, 16, v146
	v_and_b32_e32 v71, 0xffff0000, v146
	v_lshlrev_b32_e32 v72, 16, v147
	v_and_b32_e32 v73, 0xffff0000, v147
	v_pk_mul_f32 v[58:59], v[86:87], v[58:59]
	v_pk_mul_f32 v[60:61], v[88:89], v[60:61]
	v_pk_fma_f32 v[54:55], v[54:55], v[82:83], v[58:59]
	v_pk_fma_f32 v[56:57], v[56:57], v[84:85], v[60:61]
	v_pk_mul_f32 v[58:59], v[74:75], v[70:71]
	v_pk_mul_f32 v[60:61], v[76:77], v[72:73]
	v_pk_fma_f32 v[58:59], v[50:51], v[78:79], v[58:59]
	v_pk_fma_f32 v[60:61], v[52:53], v[80:81], v[60:61]
	v_cvt_pk_bf16_f32 v50, v54, v55
	v_cvt_pk_bf16_f32 v51, v56, v57
	v_cvt_pk_bf16_f32 v52, v58, v59
	s_nop 0
	v_cvt_pk_bf16_f32 v53, v60, v61
	global_store_dwordx4 v[138:139], v[50:53], off
	s_nop 1
	v_pk_mul_f32 v[50:51], v[68:69], v[56:57]
	v_pk_mul_f32 v[52:53], v[66:67], v[54:55]
	v_mul_f32_e32 v51, v51, v51
	v_mul_f32_e32 v53, v53, v53
	v_pk_mul_f32 v[56:57], v[62:63], v[58:59]
	v_fmac_f32_e32 v53, v52, v52
	v_fmac_f32_e32 v51, v50, v50
	v_add_f32_e32 v50, v53, v51
	v_mul_f32_e32 v51, v57, v57
	v_pk_mul_f32 v[54:55], v[64:65], v[60:61]
	v_fmac_f32_e32 v51, v56, v56
	v_add_f32_e32 v50, v51, v50
	v_mul_f32_e32 v51, v55, v55
	v_fmac_f32_e32 v51, v54, v54
	v_add_f32_e32 v50, v51, v50
	v_add_f32_e32 v50, v140, v50
	ds_bpermute_b32 v51, v162, v50
	s_waitcnt lgkmcnt(0)
	v_add_f32_e32 v50, v50, v51
	ds_bpermute_b32 v51, v163, v50
	s_and_saveexec_b64 s[54:55], s[36:37]
	s_cbranch_execz .LBB0_389
	v_add_u32_e32 v52, 0x80, v216
	v_ashrrev_i32_e32 v53, 31, v52
	v_readlane_b32 s28, v252, 39
	s_waitcnt lgkmcnt(0)
	v_add_f32_e32 v54, v50, v51
	v_lshlrev_b64 v[50:51], 6, v[52:53]
	v_readlane_b32 s29, v252, 40
	s_lshl_b32 s62, s74, 2
	s_nop 0
	v_lshl_add_u64 v[50:51], s[28:29], 0, v[50:51]
	v_lshl_add_u64 v[50:51], s[52:53], 2, v[50:51]
	v_lshl_add_u64 v[50:51], v[50:51], 0, s[62:63]
	global_store_dword v[50:51], v54, off
